# speedup vs baseline: 1.0114x; 1.0051x over previous
; __device__ __forceinline__ float bflo(unsigned u) { return __uint_as_float(u << 16); }
; __device__ __forceinline__ float bfhi(unsigned u) { return __uint_as_float(u & 0xffff0000u); }
; __device__ __forceinline__ void phase_peer_u(const Params& p, int layer, int xs, int wid0, int wstride, char* smraw) {
;     ...
;     int xq[8]; float sx; int sumx = 0;
;     {
;       const float x0 = bflo(xv[0]), x1 = bfhi(xv[0]), x2 = bflo(xv[1]), x3 = bfhi(xv[1]);
;       float mx = fmaxf(fmaxf(fabsf(x0), fabsf(x1)), fmaxf(fabsf(x2), fabsf(x3)));
; #pragma unroll
;       for (int m = 32; m >= 1; m >>= 1) mx = fmaxf(mx, __shfl_xor(mx, m));
;       const float inv = mx > 0.f ? 127.f / mx : 0.f;
;       sx = mx * (1.f / 127.f);
;       const int q0 = __float2int_rn(x0 * inv), q1 = __float2int_rn(x1 * inv), q2 = __float2int_rn(x2 * inv), q3 = __float2int_rn(x3 * inv);
;       asm volatile("" ::: "memory");
;       *(int*)(xqs + l * 4) = (q0 & 0xff) | ((q1 & 0xff) << 8) | ((q2 & 0xff) << 16) | ((q3 & 0xff) << 24);
;       asm volatile("" ::: "memory");
;       __builtin_amdgcn_wave_barrier();
;       asm volatile("" ::: "memory");
;       const u32x4 xa = *(const u32x4*)(xqs + j * 32), xb = *(const u32x4*)(xqs + j * 32 + 16);
;       asm volatile("" ::: "memory");
; #pragma unroll
;       for (int m = 0; m < 4; ++m) { xq[m] = (int)xa[m]; xq[4 + m] = (int)xb[m]; }
; #pragma unroll
;       for (int m = 0; m < 8; ++m) sumx = __builtin_amdgcn_sdot4(xq[m], 0x01010101, sumx, false);
;     }
;     const int corr = 8 * sumx;
;     float pr[16];
; #pragma unroll
;     for (int i = 0; i < 16; ++i) {
;       int a = 0;
; #pragma unroll
;       for (int m = 0; m < 4; ++m) {
;         const unsigned dw = q[i][m];
;         a = __builtin_amdgcn_sdot4((int)(dw & 0x0f0f0f0fu), xq[2 * m], a, false);
;         a = __builtin_amdgcn_sdot4((int)((dw >> 4) & 0x0f0f0f0fu), xq[2 * m + 1], a, false);
;       }
;       a -= corr;
;       a += __builtin_amdgcn_update_dpp(0, a, 0xB1, 0xF, 0xF, true);
;       a += __builtin_amdgcn_update_dpp(0, a, 0x4E, 0xF, 0xF, true);
;       a += __builtin_amdgcn_update_dpp(0, a, 0x141, 0xF, 0xF, true);
;       pr[i] = (float)a * sx;
;     }
.Lmy_pu0_noissueA:
	v_lshlrev_b32_e32 v40, 16, v26
	v_and_b32_e32 v41, 0xffff0000, v26
	v_lshlrev_b32_e32 v42, 16, v27
	v_and_b32_e32 v43, 0xffff0000, v27
	v_max_f32_e64 v44, |v40|, |v41|
	v_max3_f32 v44, |v42|, |v43|, v44
	s_nop 1
	v_max_f32_dpp v44, v44, v44 quad_perm:[1,0,3,2] row_mask:0xf bank_mask:0xf bound_ctrl:1
	s_nop 1
	v_max_f32_dpp v44, v44, v44 quad_perm:[2,3,0,1] row_mask:0xf bank_mask:0xf bound_ctrl:1
	s_nop 1
	v_max_f32_dpp v44, v44, v44 row_half_mirror row_mask:0xf bank_mask:0xf bound_ctrl:1
	s_nop 1
	v_max_f32_dpp v44, v44, v44 row_mirror row_mask:0xf bank_mask:0xf bound_ctrl:1
	s_nop 0
	v_readlane_b32 s6, v44, 0
	v_readlane_b32 s7, v44, 16
	v_readlane_b32 s10, v44, 32
	v_readlane_b32 s11, v44, 48
	s_nop 1
	v_mov_b32_e32 v45, s6
	v_max_f32_e32 v45, s7, v45
	v_max_f32_e32 v45, s10, v45
	v_max_f32_e32 v45, s11, v45
	v_div_scale_f32 v46, s[18:19], v45, v45, s69
	v_rcp_f32_e32 v47, v46
	s_nop 0
	v_fma_f32 v48, -v46, v47, 1.0
	v_fmac_f32_e32 v47, v48, v47
	v_div_scale_f32 v48, vcc, s69, v45, s69
	v_mul_f32_e32 v49, v48, v47
	v_fma_f32 v50, -v46, v49, v48
	v_fmac_f32_e32 v49, v50, v47
	v_fma_f32 v46, -v46, v49, v48
	v_div_fmas_f32 v46, v46, v47, v49
	v_div_fixup_f32 v46, v46, v45, s69
	v_cmp_lt_f32_e32 vcc, 0, v45
	v_mul_f32_e32 v52, 0x3c010204, v45
	v_mov_b32_e32 v84, 0
	v_cndmask_b32_e32 v46, 0, v46, vcc
	v_mul_f32_e32 v40, v46, v40
	v_mul_f32_e32 v41, v46, v41
	v_mul_f32_e32 v42, v46, v42
	v_mul_f32_e32 v43, v46, v43
	v_rndne_f32_e32 v40, v40
	v_rndne_f32_e32 v41, v41
	v_rndne_f32_e32 v42, v42
	v_rndne_f32_e32 v43, v43
	v_cvt_i32_f32_e32 v40, v40
	v_cvt_i32_f32_e32 v41, v41
	v_cvt_i32_f32_e32 v42, v42
	v_cvt_i32_f32_e32 v43, v43
	v_and_b32_e32 v40, 0xff, v40
	v_and_b32_e32 v41, 0xff, v41
	v_and_b32_e32 v42, 0xff, v42
	v_lshl_or_b32 v40, v41, 8, v40
	v_lshl_or_b32 v40, v42, 16, v40
	v_lshl_or_b32 v40, v43, 24, v40
	ds_write_b32 v3, v40
	ds_read_b128 v[32:35], v4
	ds_read_b128 v[36:39], v4 offset:16
	s_waitcnt lgkmcnt(0)
	v_dot4c_i32_i8_e32 v84, 0x1010101, v32
	v_dot4c_i32_i8_e32 v84, 0x1010101, v34
	v_dot4c_i32_i8_e32 v84, 0x1010101, v36
	v_dot4c_i32_i8_e32 v84, 0x1010101, v38
	v_and_b32_e32 v56, s21, v106
	v_and_b32_e32 v57, s23, v106
	v_and_b32_e32 v58, s21, v110
	v_and_b32_e32 v59, s23, v110
	v_and_b32_e32 v60, s21, v114
	v_and_b32_e32 v61, s23, v114
	v_and_b32_e32 v62, s21, v118
	v_and_b32_e32 v63, s23, v118
	v_mul_i32_i24_e32 v85, -8, v84
	v_dot4_i32_i8 v64, v56, v32, v85
	v_dot4_i32_i8 v86, v57, v33, 0
	v_dot4_i32_i8 v65, v58, v32, v85
	v_dot4_i32_i8 v87, v59, v33, 0
	v_dot4_i32_i8 v66, v60, v32, v85
	v_dot4_i32_i8 v88, v61, v33, 0
	v_dot4_i32_i8 v67, v62, v32, v85
	v_dot4_i32_i8 v89, v63, v33, 0
	v_and_b32_e32 v56, s21, v107
	v_and_b32_e32 v57, s23, v107
	v_and_b32_e32 v58, s21, v111
	v_and_b32_e32 v59, s23, v111
	v_and_b32_e32 v60, s21, v115
	v_and_b32_e32 v61, s23, v115
	v_and_b32_e32 v62, s21, v119
	v_and_b32_e32 v63, s23, v119
	v_dot4c_i32_i8_e32 v64, v56, v34
	v_dot4c_i32_i8_e32 v86, v57, v35
	v_dot4c_i32_i8_e32 v65, v58, v34
	v_dot4c_i32_i8_e32 v87, v59, v35
	v_dot4c_i32_i8_e32 v66, v60, v34
	v_dot4c_i32_i8_e32 v88, v61, v35
	v_dot4c_i32_i8_e32 v67, v62, v34
	v_dot4c_i32_i8_e32 v89, v63, v35
	v_and_b32_e32 v56, s21, v108
	v_and_b32_e32 v57, s23, v108
	v_and_b32_e32 v58, s21, v112
	v_and_b32_e32 v59, s23, v112
	v_and_b32_e32 v60, s21, v116
	v_and_b32_e32 v61, s23, v116
	v_and_b32_e32 v62, s21, v120
	v_and_b32_e32 v63, s23, v120
	v_dot4c_i32_i8_e32 v64, v56, v36
	v_dot4c_i32_i8_e32 v86, v57, v37
	v_dot4c_i32_i8_e32 v65, v58, v36
	v_dot4c_i32_i8_e32 v87, v59, v37
	v_dot4c_i32_i8_e32 v66, v60, v36
	v_dot4c_i32_i8_e32 v88, v61, v37
	v_dot4c_i32_i8_e32 v67, v62, v36
	v_dot4c_i32_i8_e32 v89, v63, v37
	v_and_b32_e32 v56, s21, v109
	v_and_b32_e32 v57, s23, v109
	v_and_b32_e32 v58, s21, v113
	v_and_b32_e32 v59, s23, v113
	v_and_b32_e32 v60, s21, v117
	v_and_b32_e32 v61, s23, v117
	v_and_b32_e32 v62, s21, v121
	v_and_b32_e32 v63, s23, v121
	v_dot4c_i32_i8_e32 v64, v56, v38
	v_dot4c_i32_i8_e32 v86, v57, v39
	v_dot4c_i32_i8_e32 v65, v58, v38
	v_dot4c_i32_i8_e32 v87, v59, v39
	v_dot4c_i32_i8_e32 v66, v60, v38
	v_dot4c_i32_i8_e32 v88, v61, v39
	v_dot4c_i32_i8_e32 v67, v62, v38
	v_dot4c_i32_i8_e32 v89, v63, v39
	v_ashrrev_i32_e32 v86, 4, v86
	v_ashrrev_i32_e32 v87, 4, v87
	v_ashrrev_i32_e32 v88, 4, v88
	v_ashrrev_i32_e32 v89, 4, v89
	v_add_u32_e32 v64, v64, v86
	v_add_u32_e32 v65, v65, v87
	v_add_u32_e32 v66, v66, v88
	v_add_u32_e32 v67, v67, v89
	v_add_u32_dpp v64, v64, v64 quad_perm:[1,0,3,2] row_mask:0xf bank_mask:0xf bound_ctrl:1
	v_add_u32_dpp v65, v65, v65 quad_perm:[1,0,3,2] row_mask:0xf bank_mask:0xf bound_ctrl:1
	v_add_u32_dpp v66, v66, v66 quad_perm:[1,0,3,2] row_mask:0xf bank_mask:0xf bound_ctrl:1
	v_add_u32_dpp v67, v67, v67 quad_perm:[1,0,3,2] row_mask:0xf bank_mask:0xf bound_ctrl:1
	v_add_u32_dpp v64, v64, v64 quad_perm:[2,3,0,1] row_mask:0xf bank_mask:0xf bound_ctrl:1
	v_add_u32_dpp v65, v65, v65 quad_perm:[2,3,0,1] row_mask:0xf bank_mask:0xf bound_ctrl:1
	v_add_u32_dpp v66, v66, v66 quad_perm:[2,3,0,1] row_mask:0xf bank_mask:0xf bound_ctrl:1
	v_add_u32_dpp v67, v67, v67 quad_perm:[2,3,0,1] row_mask:0xf bank_mask:0xf bound_ctrl:1
	v_add_u32_dpp v64, v64, v64 row_half_mirror row_mask:0xf bank_mask:0xf bound_ctrl:1
	v_add_u32_dpp v65, v65, v65 row_half_mirror row_mask:0xf bank_mask:0xf bound_ctrl:1
	v_add_u32_dpp v66, v66, v66 row_half_mirror row_mask:0xf bank_mask:0xf bound_ctrl:1
	v_add_u32_dpp v67, v67, v67 row_half_mirror row_mask:0xf bank_mask:0xf bound_ctrl:1
	v_cvt_f32_i32_e32 v68, v64
	v_cvt_f32_i32_e32 v69, v65
	v_cvt_f32_i32_e32 v70, v66
	v_cvt_f32_i32_e32 v71, v67
	v_pk_mul_f32 v[68:69], v[52:53], v[68:69] op_sel_hi:[0,1]
; __device__ __forceinline__ void phase_peer_u(const Params& p, int layer, int xs, int wid0, int wstride, char* smraw) {
;     ...
;     float pr[16];
; #pragma unroll
;     for (int i = 0; i < 16; ++i) {
;       int a = 0;
; #pragma unroll
;       for (int m = 0; m < 4; ++m) {
;         const unsigned dw = q[i][m];
;         a = __builtin_amdgcn_sdot4((int)(dw & 0x0f0f0f0fu), xq[2 * m], a, false);
;         a = __builtin_amdgcn_sdot4((int)((dw >> 4) & 0x0f0f0f0fu), xq[2 * m + 1], a, false);
;       }
;       a -= corr;
;       a += __builtin_amdgcn_update_dpp(0, a, 0xB1, 0xF, 0xF, true);
;       a += __builtin_amdgcn_update_dpp(0, a, 0x4E, 0xF, 0xF, true);
;       a += __builtin_amdgcn_update_dpp(0, a, 0x141, 0xF, 0xF, true);
;       pr[i] = (float)a * sx;
;     }
	v_pk_mul_f32 v[70:71], v[52:53], v[70:71] op_sel_hi:[0,1]
	v_and_b32_e32 v56, s21, v122
	v_and_b32_e32 v57, s23, v122
	v_and_b32_e32 v58, s21, v126
	v_and_b32_e32 v59, s23, v126
	v_and_b32_e32 v60, s21, v130
	v_and_b32_e32 v61, s23, v130
	v_and_b32_e32 v62, s21, v134
	v_and_b32_e32 v63, s23, v134
	v_dot4_i32_i8 v64, v56, v32, v85
	v_dot4_i32_i8 v86, v57, v33, 0
	v_dot4_i32_i8 v65, v58, v32, v85
	v_dot4_i32_i8 v87, v59, v33, 0
	v_dot4_i32_i8 v66, v60, v32, v85
	v_dot4_i32_i8 v88, v61, v33, 0
	v_dot4_i32_i8 v67, v62, v32, v85
	v_dot4_i32_i8 v89, v63, v33, 0
	v_and_b32_e32 v56, s21, v123
	v_and_b32_e32 v57, s23, v123
	v_and_b32_e32 v58, s21, v127
	v_and_b32_e32 v59, s23, v127
	v_and_b32_e32 v60, s21, v131
	v_and_b32_e32 v61, s23, v131
	v_and_b32_e32 v62, s21, v135
	v_and_b32_e32 v63, s23, v135
	v_dot4c_i32_i8_e32 v64, v56, v34
	v_dot4c_i32_i8_e32 v86, v57, v35
	v_dot4c_i32_i8_e32 v65, v58, v34
	v_dot4c_i32_i8_e32 v87, v59, v35
	v_dot4c_i32_i8_e32 v66, v60, v34
	v_dot4c_i32_i8_e32 v88, v61, v35
	v_dot4c_i32_i8_e32 v67, v62, v34
	v_dot4c_i32_i8_e32 v89, v63, v35
	v_and_b32_e32 v56, s21, v124
	v_and_b32_e32 v57, s23, v124
	v_and_b32_e32 v58, s21, v128
	v_and_b32_e32 v59, s23, v128
	v_and_b32_e32 v60, s21, v132
	v_and_b32_e32 v61, s23, v132
	v_and_b32_e32 v62, s21, v136
	v_and_b32_e32 v63, s23, v136
	v_dot4c_i32_i8_e32 v64, v56, v36
	v_dot4c_i32_i8_e32 v86, v57, v37
	v_dot4c_i32_i8_e32 v65, v58, v36
	v_dot4c_i32_i8_e32 v87, v59, v37
	v_dot4c_i32_i8_e32 v66, v60, v36
	v_dot4c_i32_i8_e32 v88, v61, v37
	v_dot4c_i32_i8_e32 v67, v62, v36
	v_dot4c_i32_i8_e32 v89, v63, v37
	v_and_b32_e32 v56, s21, v125
	v_and_b32_e32 v57, s23, v125
	v_and_b32_e32 v58, s21, v129
	v_and_b32_e32 v59, s23, v129
	v_and_b32_e32 v60, s21, v133
	v_and_b32_e32 v61, s23, v133
	v_and_b32_e32 v62, s21, v137
	v_and_b32_e32 v63, s23, v137
	v_dot4c_i32_i8_e32 v64, v56, v38
	v_dot4c_i32_i8_e32 v86, v57, v39
	v_dot4c_i32_i8_e32 v65, v58, v38
	v_dot4c_i32_i8_e32 v87, v59, v39
	v_dot4c_i32_i8_e32 v66, v60, v38
	v_dot4c_i32_i8_e32 v88, v61, v39
	v_dot4c_i32_i8_e32 v67, v62, v38
	v_dot4c_i32_i8_e32 v89, v63, v39
	v_ashrrev_i32_e32 v86, 4, v86
	v_ashrrev_i32_e32 v87, 4, v87
	v_ashrrev_i32_e32 v88, 4, v88
	v_ashrrev_i32_e32 v89, 4, v89
	v_add_u32_e32 v64, v64, v86
	v_add_u32_e32 v65, v65, v87
	v_add_u32_e32 v66, v66, v88
	v_add_u32_e32 v67, v67, v89
	v_add_u32_dpp v64, v64, v64 quad_perm:[1,0,3,2] row_mask:0xf bank_mask:0xf bound_ctrl:1
	v_add_u32_dpp v65, v65, v65 quad_perm:[1,0,3,2] row_mask:0xf bank_mask:0xf bound_ctrl:1
	v_add_u32_dpp v66, v66, v66 quad_perm:[1,0,3,2] row_mask:0xf bank_mask:0xf bound_ctrl:1
	v_add_u32_dpp v67, v67, v67 quad_perm:[1,0,3,2] row_mask:0xf bank_mask:0xf bound_ctrl:1
	v_add_u32_dpp v64, v64, v64 quad_perm:[2,3,0,1] row_mask:0xf bank_mask:0xf bound_ctrl:1
	v_add_u32_dpp v65, v65, v65 quad_perm:[2,3,0,1] row_mask:0xf bank_mask:0xf bound_ctrl:1
	v_add_u32_dpp v66, v66, v66 quad_perm:[2,3,0,1] row_mask:0xf bank_mask:0xf bound_ctrl:1
	v_add_u32_dpp v67, v67, v67 quad_perm:[2,3,0,1] row_mask:0xf bank_mask:0xf bound_ctrl:1
	v_add_u32_dpp v64, v64, v64 row_half_mirror row_mask:0xf bank_mask:0xf bound_ctrl:1
	v_add_u32_dpp v65, v65, v65 row_half_mirror row_mask:0xf bank_mask:0xf bound_ctrl:1
	v_add_u32_dpp v66, v66, v66 row_half_mirror row_mask:0xf bank_mask:0xf bound_ctrl:1
	v_add_u32_dpp v67, v67, v67 row_half_mirror row_mask:0xf bank_mask:0xf bound_ctrl:1
	v_cvt_f32_i32_e32 v72, v64
	v_cvt_f32_i32_e32 v73, v65
	v_cvt_f32_i32_e32 v74, v66
	v_cvt_f32_i32_e32 v75, v67
	v_pk_mul_f32 v[72:73], v[52:53], v[72:73] op_sel_hi:[0,1]
	v_pk_mul_f32 v[74:75], v[52:53], v[74:75] op_sel_hi:[0,1]
	v_and_b32_e32 v56, s21, v138
	v_and_b32_e32 v57, s23, v138
	v_and_b32_e32 v58, s21, v142
	v_and_b32_e32 v59, s23, v142
	v_and_b32_e32 v60, s21, v146
	v_and_b32_e32 v61, s23, v146
	v_and_b32_e32 v62, s21, v150
	v_and_b32_e32 v63, s23, v150
	v_dot4_i32_i8 v64, v56, v32, v85
	v_dot4_i32_i8 v86, v57, v33, 0
	v_dot4_i32_i8 v65, v58, v32, v85
	v_dot4_i32_i8 v87, v59, v33, 0
	v_dot4_i32_i8 v66, v60, v32, v85
	v_dot4_i32_i8 v88, v61, v33, 0
	v_dot4_i32_i8 v67, v62, v32, v85
	v_dot4_i32_i8 v89, v63, v33, 0
	v_and_b32_e32 v56, s21, v139
	v_and_b32_e32 v57, s23, v139
	v_and_b32_e32 v58, s21, v143
	v_and_b32_e32 v59, s23, v143
	v_and_b32_e32 v60, s21, v147
	v_and_b32_e32 v61, s23, v147
	v_and_b32_e32 v62, s21, v151
	v_and_b32_e32 v63, s23, v151
	v_dot4c_i32_i8_e32 v64, v56, v34
	v_dot4c_i32_i8_e32 v86, v57, v35
	v_dot4c_i32_i8_e32 v65, v58, v34
	v_dot4c_i32_i8_e32 v87, v59, v35
	v_dot4c_i32_i8_e32 v66, v60, v34
	v_dot4c_i32_i8_e32 v88, v61, v35
	v_dot4c_i32_i8_e32 v67, v62, v34
	v_dot4c_i32_i8_e32 v89, v63, v35
	v_and_b32_e32 v56, s21, v140
	v_and_b32_e32 v57, s23, v140
	v_and_b32_e32 v58, s21, v144
	v_and_b32_e32 v59, s23, v144
	v_and_b32_e32 v60, s21, v148
	v_and_b32_e32 v61, s23, v148
	v_and_b32_e32 v62, s21, v152
	v_and_b32_e32 v63, s23, v152
	v_dot4c_i32_i8_e32 v64, v56, v36
	v_dot4c_i32_i8_e32 v86, v57, v37
	v_dot4c_i32_i8_e32 v65, v58, v36
	v_dot4c_i32_i8_e32 v87, v59, v37
	v_dot4c_i32_i8_e32 v66, v60, v36
	v_dot4c_i32_i8_e32 v88, v61, v37
	v_dot4c_i32_i8_e32 v67, v62, v36
	v_dot4c_i32_i8_e32 v89, v63, v37
	v_and_b32_e32 v56, s21, v141
	v_and_b32_e32 v57, s23, v141
	v_and_b32_e32 v58, s21, v145
	v_and_b32_e32 v59, s23, v145
	v_and_b32_e32 v60, s21, v149
	v_and_b32_e32 v61, s23, v149
	v_and_b32_e32 v62, s21, v153
	v_and_b32_e32 v63, s23, v153
	v_dot4c_i32_i8_e32 v64, v56, v38
	v_dot4c_i32_i8_e32 v86, v57, v39
	v_dot4c_i32_i8_e32 v65, v58, v38
	v_dot4c_i32_i8_e32 v87, v59, v39
	v_dot4c_i32_i8_e32 v66, v60, v38
	v_dot4c_i32_i8_e32 v88, v61, v39
	v_dot4c_i32_i8_e32 v67, v62, v38
; __device__ __forceinline__ void phase_peer_u(const Params& p, int layer, int xs, int wid0, int wstride, char* smraw) {
;     ...
;     float pr[16];
; #pragma unroll
;     for (int i = 0; i < 16; ++i) {
;       int a = 0;
; #pragma unroll
;       for (int m = 0; m < 4; ++m) {
;         const unsigned dw = q[i][m];
;         a = __builtin_amdgcn_sdot4((int)(dw & 0x0f0f0f0fu), xq[2 * m], a, false);
;         a = __builtin_amdgcn_sdot4((int)((dw >> 4) & 0x0f0f0f0fu), xq[2 * m + 1], a, false);
;       }
;       a -= corr;
;       a += __builtin_amdgcn_update_dpp(0, a, 0xB1, 0xF, 0xF, true);
;       a += __builtin_amdgcn_update_dpp(0, a, 0x4E, 0xF, 0xF, true);
;       a += __builtin_amdgcn_update_dpp(0, a, 0x141, 0xF, 0xF, true);
;       pr[i] = (float)a * sx;
;     }
;     if (j == 0) {
;       f32x4* dst = (f32x4*)((char*)p.actp + ((unsigned)t * 4096u + (unsigned)(sl * 512 + g * 64)));
; #pragma unroll
;       for (int q4 = 0; q4 < 4; ++q4) dst[q4] = f32x4{pr[q4 * 4], pr[q4 * 4 + 1], pr[q4 * 4 + 2], pr[q4 * 4 + 3]};
;     }
	v_dot4c_i32_i8_e32 v89, v63, v39
	v_ashrrev_i32_e32 v86, 4, v86
	v_ashrrev_i32_e32 v87, 4, v87
	v_ashrrev_i32_e32 v88, 4, v88
	v_ashrrev_i32_e32 v89, 4, v89
	v_add_u32_e32 v64, v64, v86
	v_add_u32_e32 v65, v65, v87
	v_add_u32_e32 v66, v66, v88
	v_add_u32_e32 v67, v67, v89
	v_add_u32_dpp v64, v64, v64 quad_perm:[1,0,3,2] row_mask:0xf bank_mask:0xf bound_ctrl:1
	v_add_u32_dpp v65, v65, v65 quad_perm:[1,0,3,2] row_mask:0xf bank_mask:0xf bound_ctrl:1
	v_add_u32_dpp v66, v66, v66 quad_perm:[1,0,3,2] row_mask:0xf bank_mask:0xf bound_ctrl:1
	v_add_u32_dpp v67, v67, v67 quad_perm:[1,0,3,2] row_mask:0xf bank_mask:0xf bound_ctrl:1
	v_add_u32_dpp v64, v64, v64 quad_perm:[2,3,0,1] row_mask:0xf bank_mask:0xf bound_ctrl:1
	v_add_u32_dpp v65, v65, v65 quad_perm:[2,3,0,1] row_mask:0xf bank_mask:0xf bound_ctrl:1
	v_add_u32_dpp v66, v66, v66 quad_perm:[2,3,0,1] row_mask:0xf bank_mask:0xf bound_ctrl:1
	v_add_u32_dpp v67, v67, v67 quad_perm:[2,3,0,1] row_mask:0xf bank_mask:0xf bound_ctrl:1
	v_add_u32_dpp v64, v64, v64 row_half_mirror row_mask:0xf bank_mask:0xf bound_ctrl:1
	v_add_u32_dpp v65, v65, v65 row_half_mirror row_mask:0xf bank_mask:0xf bound_ctrl:1
	v_add_u32_dpp v66, v66, v66 row_half_mirror row_mask:0xf bank_mask:0xf bound_ctrl:1
	v_add_u32_dpp v67, v67, v67 row_half_mirror row_mask:0xf bank_mask:0xf bound_ctrl:1
	v_cvt_f32_i32_e32 v76, v64
	v_cvt_f32_i32_e32 v77, v65
	v_cvt_f32_i32_e32 v78, v66
	v_cvt_f32_i32_e32 v79, v67
	v_pk_mul_f32 v[76:77], v[52:53], v[76:77] op_sel_hi:[0,1]
	v_pk_mul_f32 v[78:79], v[52:53], v[78:79] op_sel_hi:[0,1]
	v_and_b32_e32 v56, s21, v154
	v_and_b32_e32 v57, s23, v154
	v_and_b32_e32 v58, s21, v158
	v_and_b32_e32 v59, s23, v158
	v_and_b32_e32 v60, s21, v162
	v_and_b32_e32 v61, s23, v162
	v_and_b32_e32 v62, s21, v166
	v_and_b32_e32 v63, s23, v166
	v_dot4_i32_i8 v64, v56, v32, v85
	v_dot4_i32_i8 v86, v57, v33, 0
	v_dot4_i32_i8 v65, v58, v32, v85
	v_dot4_i32_i8 v87, v59, v33, 0
	v_dot4_i32_i8 v66, v60, v32, v85
	v_dot4_i32_i8 v88, v61, v33, 0
	v_dot4_i32_i8 v67, v62, v32, v85
	v_dot4_i32_i8 v89, v63, v33, 0
	v_and_b32_e32 v56, s21, v155
	v_and_b32_e32 v57, s23, v155
	v_and_b32_e32 v58, s21, v159
	v_and_b32_e32 v59, s23, v159
	v_and_b32_e32 v60, s21, v163
	v_and_b32_e32 v61, s23, v163
	v_and_b32_e32 v62, s21, v167
	v_and_b32_e32 v63, s23, v167
	v_dot4c_i32_i8_e32 v64, v56, v34
	v_dot4c_i32_i8_e32 v86, v57, v35
	v_dot4c_i32_i8_e32 v65, v58, v34
	v_dot4c_i32_i8_e32 v87, v59, v35
	v_dot4c_i32_i8_e32 v66, v60, v34
	v_dot4c_i32_i8_e32 v88, v61, v35
	v_dot4c_i32_i8_e32 v67, v62, v34
	v_dot4c_i32_i8_e32 v89, v63, v35
	v_and_b32_e32 v56, s21, v156
	v_and_b32_e32 v57, s23, v156
	v_and_b32_e32 v58, s21, v160
	v_and_b32_e32 v59, s23, v160
	v_and_b32_e32 v60, s21, v164
	v_and_b32_e32 v61, s23, v164
	v_and_b32_e32 v62, s21, v168
	v_and_b32_e32 v63, s23, v168
	v_dot4c_i32_i8_e32 v64, v56, v36
	v_dot4c_i32_i8_e32 v86, v57, v37
	v_dot4c_i32_i8_e32 v65, v58, v36
	v_dot4c_i32_i8_e32 v87, v59, v37
	v_dot4c_i32_i8_e32 v66, v60, v36
	v_dot4c_i32_i8_e32 v88, v61, v37
	v_dot4c_i32_i8_e32 v67, v62, v36
	v_dot4c_i32_i8_e32 v89, v63, v37
	v_and_b32_e32 v56, s21, v157
	v_and_b32_e32 v57, s23, v157
	v_and_b32_e32 v58, s21, v161
	v_and_b32_e32 v59, s23, v161
	v_and_b32_e32 v60, s21, v165
	v_and_b32_e32 v61, s23, v165
	v_and_b32_e32 v62, s21, v169
	v_and_b32_e32 v63, s23, v169
	v_dot4c_i32_i8_e32 v64, v56, v38
	v_dot4c_i32_i8_e32 v86, v57, v39
	v_dot4c_i32_i8_e32 v65, v58, v38
	v_dot4c_i32_i8_e32 v87, v59, v39
	v_dot4c_i32_i8_e32 v66, v60, v38
	v_dot4c_i32_i8_e32 v88, v61, v39
	v_dot4c_i32_i8_e32 v67, v62, v38
	v_dot4c_i32_i8_e32 v89, v63, v39
	v_ashrrev_i32_e32 v86, 4, v86
	v_ashrrev_i32_e32 v87, 4, v87
	v_ashrrev_i32_e32 v88, 4, v88
	v_ashrrev_i32_e32 v89, 4, v89
	v_add_u32_e32 v64, v64, v86
	v_add_u32_e32 v65, v65, v87
	v_add_u32_e32 v66, v66, v88
	v_add_u32_e32 v67, v67, v89
	v_add_u32_dpp v64, v64, v64 quad_perm:[1,0,3,2] row_mask:0xf bank_mask:0xf bound_ctrl:1
	v_add_u32_dpp v65, v65, v65 quad_perm:[1,0,3,2] row_mask:0xf bank_mask:0xf bound_ctrl:1
	v_add_u32_dpp v66, v66, v66 quad_perm:[1,0,3,2] row_mask:0xf bank_mask:0xf bound_ctrl:1
	v_add_u32_dpp v67, v67, v67 quad_perm:[1,0,3,2] row_mask:0xf bank_mask:0xf bound_ctrl:1
	v_add_u32_dpp v64, v64, v64 quad_perm:[2,3,0,1] row_mask:0xf bank_mask:0xf bound_ctrl:1
	v_add_u32_dpp v65, v65, v65 quad_perm:[2,3,0,1] row_mask:0xf bank_mask:0xf bound_ctrl:1
	v_add_u32_dpp v66, v66, v66 quad_perm:[2,3,0,1] row_mask:0xf bank_mask:0xf bound_ctrl:1
	v_add_u32_dpp v67, v67, v67 quad_perm:[2,3,0,1] row_mask:0xf bank_mask:0xf bound_ctrl:1
	v_add_u32_dpp v64, v64, v64 row_half_mirror row_mask:0xf bank_mask:0xf bound_ctrl:1
	v_add_u32_dpp v65, v65, v65 row_half_mirror row_mask:0xf bank_mask:0xf bound_ctrl:1
	v_add_u32_dpp v66, v66, v66 row_half_mirror row_mask:0xf bank_mask:0xf bound_ctrl:1
	v_add_u32_dpp v67, v67, v67 row_half_mirror row_mask:0xf bank_mask:0xf bound_ctrl:1
	v_cvt_f32_i32_e32 v80, v64
	v_cvt_f32_i32_e32 v81, v65
	v_cvt_f32_i32_e32 v82, v66
	v_cvt_f32_i32_e32 v83, v67
	v_pk_mul_f32 v[80:81], v[52:53], v[80:81] op_sel_hi:[0,1]
	v_pk_mul_f32 v[82:83], v[52:53], v[82:83] op_sel_hi:[0,1]
	s_lshl_b32 s70, s60, 1
	s_add_u32 s70, s70, s28
	s_lshl_b32 s70, s70, 12
	s_add_u32 s70, s70, s68
	s_mov_b64 s[74:75], exec
	s_and_b64 exec, exec, s[72:73]
	v_add_u32_e32 v9, s70, v5
	global_store_dwordx4 v9, v[68:71], s[64:65]
	global_store_dwordx4 v9, v[72:75], s[64:65] offset:16
	global_store_dwordx4 v9, v[76:79], s[64:65] offset:32
	global_store_dwordx4 v9, v[80:83], s[64:65] offset:48
	s_mov_b64 exec, s[74:75]
	s_mov_b32 s60, s62
	s_cmp_lt_u32 s60, s61
	s_cbranch_scc0 .Lmy_pu0_done

; __device__ __forceinline__ float bflo(unsigned u) { return __uint_as_float(u << 16); }
; __device__ __forceinline__ float bfhi(unsigned u) { return __uint_as_float(u & 0xffff0000u); }
; __device__ __forceinline__ void phase_peer_u(const Params& p, int layer, int xs, int wid0, int wstride, char* smraw) {
;     ...
;     int xq[8]; float sx; int sumx = 0;
;     {
;       const float x0 = bflo(xv[0]), x1 = bfhi(xv[0]), x2 = bflo(xv[1]), x3 = bfhi(xv[1]);
;       float mx = fmaxf(fmaxf(fabsf(x0), fabsf(x1)), fmaxf(fabsf(x2), fabsf(x3)));
; #pragma unroll
;       for (int m = 32; m >= 1; m >>= 1) mx = fmaxf(mx, __shfl_xor(mx, m));
;       const float inv = mx > 0.f ? 127.f / mx : 0.f;
;       sx = mx * (1.f / 127.f);
;       const int q0 = __float2int_rn(x0 * inv), q1 = __float2int_rn(x1 * inv), q2 = __float2int_rn(x2 * inv), q3 = __float2int_rn(x3 * inv);
;       asm volatile("" ::: "memory");
;       *(int*)(xqs + l * 4) = (q0 & 0xff) | ((q1 & 0xff) << 8) | ((q2 & 0xff) << 16) | ((q3 & 0xff) << 24);
;       asm volatile("" ::: "memory");
;       __builtin_amdgcn_wave_barrier();
;       asm volatile("" ::: "memory");
;       const u32x4 xa = *(const u32x4*)(xqs + j * 32), xb = *(const u32x4*)(xqs + j * 32 + 16);
;       asm volatile("" ::: "memory");
; #pragma unroll
;       for (int m = 0; m < 4; ++m) { xq[m] = (int)xa[m]; xq[4 + m] = (int)xb[m]; }
; #pragma unroll
;       for (int m = 0; m < 8; ++m) sumx = __builtin_amdgcn_sdot4(xq[m], 0x01010101, sumx, false);
;     }
;     const int corr = 8 * sumx;
;     float pr[16];
; #pragma unroll
;     for (int i = 0; i < 16; ++i) {
;       int a = 0;
; #pragma unroll
;       for (int m = 0; m < 4; ++m) {
;         const unsigned dw = q[i][m];
;         a = __builtin_amdgcn_sdot4((int)(dw & 0x0f0f0f0fu), xq[2 * m], a, false);
;         a = __builtin_amdgcn_sdot4((int)((dw >> 4) & 0x0f0f0f0fu), xq[2 * m + 1], a, false);
;       }
;       a -= corr;
;       a += __builtin_amdgcn_update_dpp(0, a, 0xB1, 0xF, 0xF, true);
;       a += __builtin_amdgcn_update_dpp(0, a, 0x4E, 0xF, 0xF, true);
;       a += __builtin_amdgcn_update_dpp(0, a, 0x141, 0xF, 0xF, true);
;       pr[i] = (float)a * sx;
;     }
.Lmy_pu0_noissueB:
	v_lshlrev_b32_e32 v40, 16, v28
	v_and_b32_e32 v41, 0xffff0000, v28
	v_lshlrev_b32_e32 v42, 16, v29
	v_and_b32_e32 v43, 0xffff0000, v29
	v_max_f32_e64 v44, |v40|, |v41|
	v_max3_f32 v44, |v42|, |v43|, v44
	s_nop 1
	v_max_f32_dpp v44, v44, v44 quad_perm:[1,0,3,2] row_mask:0xf bank_mask:0xf bound_ctrl:1
	s_nop 1
	v_max_f32_dpp v44, v44, v44 quad_perm:[2,3,0,1] row_mask:0xf bank_mask:0xf bound_ctrl:1
	s_nop 1
	v_max_f32_dpp v44, v44, v44 row_half_mirror row_mask:0xf bank_mask:0xf bound_ctrl:1
	s_nop 1
	v_max_f32_dpp v44, v44, v44 row_mirror row_mask:0xf bank_mask:0xf bound_ctrl:1
	s_nop 0
	v_readlane_b32 s6, v44, 0
	v_readlane_b32 s7, v44, 16
	v_readlane_b32 s10, v44, 32
	v_readlane_b32 s11, v44, 48
	s_nop 1
	v_mov_b32_e32 v45, s6
	v_max_f32_e32 v45, s7, v45
	v_max_f32_e32 v45, s10, v45
	v_max_f32_e32 v45, s11, v45
	v_div_scale_f32 v46, s[18:19], v45, v45, s69
	v_rcp_f32_e32 v47, v46
	s_nop 0
	v_fma_f32 v48, -v46, v47, 1.0
	v_fmac_f32_e32 v47, v48, v47
	v_div_scale_f32 v48, vcc, s69, v45, s69
	v_mul_f32_e32 v49, v48, v47
	v_fma_f32 v50, -v46, v49, v48
	v_fmac_f32_e32 v49, v50, v47
	v_fma_f32 v46, -v46, v49, v48
	v_div_fmas_f32 v46, v46, v47, v49
	v_div_fixup_f32 v46, v46, v45, s69
	v_cmp_lt_f32_e32 vcc, 0, v45
	v_mul_f32_e32 v52, 0x3c010204, v45
	v_mov_b32_e32 v84, 0
	v_cndmask_b32_e32 v46, 0, v46, vcc
	v_mul_f32_e32 v40, v46, v40
	v_mul_f32_e32 v41, v46, v41
	v_mul_f32_e32 v42, v46, v42
	v_mul_f32_e32 v43, v46, v43
	v_rndne_f32_e32 v40, v40
	v_rndne_f32_e32 v41, v41
	v_rndne_f32_e32 v42, v42
	v_rndne_f32_e32 v43, v43
	v_cvt_i32_f32_e32 v40, v40
	v_cvt_i32_f32_e32 v41, v41
	v_cvt_i32_f32_e32 v42, v42
	v_cvt_i32_f32_e32 v43, v43
	v_and_b32_e32 v40, 0xff, v40
	v_and_b32_e32 v41, 0xff, v41
	v_and_b32_e32 v42, 0xff, v42
	v_lshl_or_b32 v40, v41, 8, v40
	v_lshl_or_b32 v40, v42, 16, v40
	v_lshl_or_b32 v40, v43, 24, v40
	ds_write_b32 v3, v40
	ds_read_b128 v[32:35], v4
	ds_read_b128 v[36:39], v4 offset:16
	s_waitcnt lgkmcnt(0)
	v_dot4c_i32_i8_e32 v84, 0x1010101, v32
	v_dot4c_i32_i8_e32 v84, 0x1010101, v34
	v_dot4c_i32_i8_e32 v84, 0x1010101, v36
	v_dot4c_i32_i8_e32 v84, 0x1010101, v38
	v_and_b32_e32 v56, s21, v170
	v_and_b32_e32 v57, s23, v170
	v_and_b32_e32 v58, s21, v174
	v_and_b32_e32 v59, s23, v174
	v_and_b32_e32 v60, s21, v178
	v_and_b32_e32 v61, s23, v178
	v_and_b32_e32 v62, s21, v182
	v_and_b32_e32 v63, s23, v182
	v_mul_i32_i24_e32 v85, -8, v84
	v_dot4_i32_i8 v64, v56, v32, v85
	v_dot4_i32_i8 v86, v57, v33, 0
	v_dot4_i32_i8 v65, v58, v32, v85
	v_dot4_i32_i8 v87, v59, v33, 0
	v_dot4_i32_i8 v66, v60, v32, v85
	v_dot4_i32_i8 v88, v61, v33, 0
	v_dot4_i32_i8 v67, v62, v32, v85
	v_dot4_i32_i8 v89, v63, v33, 0
	v_and_b32_e32 v56, s21, v171
	v_and_b32_e32 v57, s23, v171
	v_and_b32_e32 v58, s21, v175
	v_and_b32_e32 v59, s23, v175
	v_and_b32_e32 v60, s21, v179
	v_and_b32_e32 v61, s23, v179
	v_and_b32_e32 v62, s21, v183
	v_and_b32_e32 v63, s23, v183
	v_dot4c_i32_i8_e32 v64, v56, v34
	v_dot4c_i32_i8_e32 v86, v57, v35
	v_dot4c_i32_i8_e32 v65, v58, v34
	v_dot4c_i32_i8_e32 v87, v59, v35
	v_dot4c_i32_i8_e32 v66, v60, v34
	v_dot4c_i32_i8_e32 v88, v61, v35
	v_dot4c_i32_i8_e32 v67, v62, v34
	v_dot4c_i32_i8_e32 v89, v63, v35
	v_and_b32_e32 v56, s21, v172
	v_and_b32_e32 v57, s23, v172
	v_and_b32_e32 v58, s21, v176
	v_and_b32_e32 v59, s23, v176
	v_and_b32_e32 v60, s21, v180
	v_and_b32_e32 v61, s23, v180
	v_and_b32_e32 v62, s21, v184
	v_and_b32_e32 v63, s23, v184
	v_dot4c_i32_i8_e32 v64, v56, v36
	v_dot4c_i32_i8_e32 v86, v57, v37
	v_dot4c_i32_i8_e32 v65, v58, v36
	v_dot4c_i32_i8_e32 v87, v59, v37
	v_dot4c_i32_i8_e32 v66, v60, v36
	v_dot4c_i32_i8_e32 v88, v61, v37
	v_dot4c_i32_i8_e32 v67, v62, v36
	v_dot4c_i32_i8_e32 v89, v63, v37
	v_and_b32_e32 v56, s21, v173
	v_and_b32_e32 v57, s23, v173
	v_and_b32_e32 v58, s21, v177
	v_and_b32_e32 v59, s23, v177
	v_and_b32_e32 v60, s21, v181
	v_and_b32_e32 v61, s23, v181
	v_and_b32_e32 v62, s21, v185
	v_and_b32_e32 v63, s23, v185
	v_dot4c_i32_i8_e32 v64, v56, v38
	v_dot4c_i32_i8_e32 v86, v57, v39
	v_dot4c_i32_i8_e32 v65, v58, v38
	v_dot4c_i32_i8_e32 v87, v59, v39
	v_dot4c_i32_i8_e32 v66, v60, v38
	v_dot4c_i32_i8_e32 v88, v61, v39
	v_dot4c_i32_i8_e32 v67, v62, v38
	v_dot4c_i32_i8_e32 v89, v63, v39
	v_ashrrev_i32_e32 v86, 4, v86
	v_ashrrev_i32_e32 v87, 4, v87
	v_ashrrev_i32_e32 v88, 4, v88
	v_ashrrev_i32_e32 v89, 4, v89
	v_add_u32_e32 v64, v64, v86
	v_add_u32_e32 v65, v65, v87
	v_add_u32_e32 v66, v66, v88
	v_add_u32_e32 v67, v67, v89
	v_add_u32_dpp v64, v64, v64 quad_perm:[1,0,3,2] row_mask:0xf bank_mask:0xf bound_ctrl:1
	v_add_u32_dpp v65, v65, v65 quad_perm:[1,0,3,2] row_mask:0xf bank_mask:0xf bound_ctrl:1
	v_add_u32_dpp v66, v66, v66 quad_perm:[1,0,3,2] row_mask:0xf bank_mask:0xf bound_ctrl:1
	v_add_u32_dpp v67, v67, v67 quad_perm:[1,0,3,2] row_mask:0xf bank_mask:0xf bound_ctrl:1
	v_add_u32_dpp v64, v64, v64 quad_perm:[2,3,0,1] row_mask:0xf bank_mask:0xf bound_ctrl:1
	v_add_u32_dpp v65, v65, v65 quad_perm:[2,3,0,1] row_mask:0xf bank_mask:0xf bound_ctrl:1
	v_add_u32_dpp v66, v66, v66 quad_perm:[2,3,0,1] row_mask:0xf bank_mask:0xf bound_ctrl:1
	v_add_u32_dpp v67, v67, v67 quad_perm:[2,3,0,1] row_mask:0xf bank_mask:0xf bound_ctrl:1
	v_add_u32_dpp v64, v64, v64 row_half_mirror row_mask:0xf bank_mask:0xf bound_ctrl:1
	v_add_u32_dpp v65, v65, v65 row_half_mirror row_mask:0xf bank_mask:0xf bound_ctrl:1
	v_add_u32_dpp v66, v66, v66 row_half_mirror row_mask:0xf bank_mask:0xf bound_ctrl:1
	v_add_u32_dpp v67, v67, v67 row_half_mirror row_mask:0xf bank_mask:0xf bound_ctrl:1
	v_cvt_f32_i32_e32 v68, v64
	v_cvt_f32_i32_e32 v69, v65
	v_cvt_f32_i32_e32 v70, v66
	v_cvt_f32_i32_e32 v71, v67
	v_pk_mul_f32 v[68:69], v[52:53], v[68:69] op_sel_hi:[0,1]
; __device__ __forceinline__ void phase_peer_u(const Params& p, int layer, int xs, int wid0, int wstride, char* smraw) {
;     ...
;     float pr[16];
; #pragma unroll
;     for (int i = 0; i < 16; ++i) {
;       int a = 0;
; #pragma unroll
;       for (int m = 0; m < 4; ++m) {
;         const unsigned dw = q[i][m];
;         a = __builtin_amdgcn_sdot4((int)(dw & 0x0f0f0f0fu), xq[2 * m], a, false);
;         a = __builtin_amdgcn_sdot4((int)((dw >> 4) & 0x0f0f0f0fu), xq[2 * m + 1], a, false);
;       }
;       a -= corr;
;       a += __builtin_amdgcn_update_dpp(0, a, 0xB1, 0xF, 0xF, true);
;       a += __builtin_amdgcn_update_dpp(0, a, 0x4E, 0xF, 0xF, true);
;       a += __builtin_amdgcn_update_dpp(0, a, 0x141, 0xF, 0xF, true);
;       pr[i] = (float)a * sx;
;     }
	v_pk_mul_f32 v[70:71], v[52:53], v[70:71] op_sel_hi:[0,1]
	v_and_b32_e32 v56, s21, v192
	v_and_b32_e32 v57, s23, v192
	v_and_b32_e32 v58, s21, v196
	v_and_b32_e32 v59, s23, v196
	v_and_b32_e32 v60, s21, v200
	v_and_b32_e32 v61, s23, v200
	v_and_b32_e32 v62, s21, v204
	v_and_b32_e32 v63, s23, v204
	v_dot4_i32_i8 v64, v56, v32, v85
	v_dot4_i32_i8 v86, v57, v33, 0
	v_dot4_i32_i8 v65, v58, v32, v85
	v_dot4_i32_i8 v87, v59, v33, 0
	v_dot4_i32_i8 v66, v60, v32, v85
	v_dot4_i32_i8 v88, v61, v33, 0
	v_dot4_i32_i8 v67, v62, v32, v85
	v_dot4_i32_i8 v89, v63, v33, 0
	v_and_b32_e32 v56, s21, v193
	v_and_b32_e32 v57, s23, v193
	v_and_b32_e32 v58, s21, v197
	v_and_b32_e32 v59, s23, v197
	v_and_b32_e32 v60, s21, v201
	v_and_b32_e32 v61, s23, v201
	v_and_b32_e32 v62, s21, v205
	v_and_b32_e32 v63, s23, v205
	v_dot4c_i32_i8_e32 v64, v56, v34
	v_dot4c_i32_i8_e32 v86, v57, v35
	v_dot4c_i32_i8_e32 v65, v58, v34
	v_dot4c_i32_i8_e32 v87, v59, v35
	v_dot4c_i32_i8_e32 v66, v60, v34
	v_dot4c_i32_i8_e32 v88, v61, v35
	v_dot4c_i32_i8_e32 v67, v62, v34
	v_dot4c_i32_i8_e32 v89, v63, v35
	v_and_b32_e32 v56, s21, v194
	v_and_b32_e32 v57, s23, v194
	v_and_b32_e32 v58, s21, v198
	v_and_b32_e32 v59, s23, v198
	v_and_b32_e32 v60, s21, v202
	v_and_b32_e32 v61, s23, v202
	v_and_b32_e32 v62, s21, v206
	v_and_b32_e32 v63, s23, v206
	v_dot4c_i32_i8_e32 v64, v56, v36
	v_dot4c_i32_i8_e32 v86, v57, v37
	v_dot4c_i32_i8_e32 v65, v58, v36
	v_dot4c_i32_i8_e32 v87, v59, v37
	v_dot4c_i32_i8_e32 v66, v60, v36
	v_dot4c_i32_i8_e32 v88, v61, v37
	v_dot4c_i32_i8_e32 v67, v62, v36
	v_dot4c_i32_i8_e32 v89, v63, v37
	v_and_b32_e32 v56, s21, v195
	v_and_b32_e32 v57, s23, v195
	v_and_b32_e32 v58, s21, v199
	v_and_b32_e32 v59, s23, v199
	v_and_b32_e32 v60, s21, v203
	v_and_b32_e32 v61, s23, v203
	v_and_b32_e32 v62, s21, v207
	v_and_b32_e32 v63, s23, v207
	v_dot4c_i32_i8_e32 v64, v56, v38
	v_dot4c_i32_i8_e32 v86, v57, v39
	v_dot4c_i32_i8_e32 v65, v58, v38
	v_dot4c_i32_i8_e32 v87, v59, v39
	v_dot4c_i32_i8_e32 v66, v60, v38
	v_dot4c_i32_i8_e32 v88, v61, v39
	v_dot4c_i32_i8_e32 v67, v62, v38
	v_dot4c_i32_i8_e32 v89, v63, v39
	v_ashrrev_i32_e32 v86, 4, v86
	v_ashrrev_i32_e32 v87, 4, v87
	v_ashrrev_i32_e32 v88, 4, v88
	v_ashrrev_i32_e32 v89, 4, v89
	v_add_u32_e32 v64, v64, v86
	v_add_u32_e32 v65, v65, v87
	v_add_u32_e32 v66, v66, v88
	v_add_u32_e32 v67, v67, v89
	v_add_u32_dpp v64, v64, v64 quad_perm:[1,0,3,2] row_mask:0xf bank_mask:0xf bound_ctrl:1
	v_add_u32_dpp v65, v65, v65 quad_perm:[1,0,3,2] row_mask:0xf bank_mask:0xf bound_ctrl:1
	v_add_u32_dpp v66, v66, v66 quad_perm:[1,0,3,2] row_mask:0xf bank_mask:0xf bound_ctrl:1
	v_add_u32_dpp v67, v67, v67 quad_perm:[1,0,3,2] row_mask:0xf bank_mask:0xf bound_ctrl:1
	v_add_u32_dpp v64, v64, v64 quad_perm:[2,3,0,1] row_mask:0xf bank_mask:0xf bound_ctrl:1
	v_add_u32_dpp v65, v65, v65 quad_perm:[2,3,0,1] row_mask:0xf bank_mask:0xf bound_ctrl:1
	v_add_u32_dpp v66, v66, v66 quad_perm:[2,3,0,1] row_mask:0xf bank_mask:0xf bound_ctrl:1
	v_add_u32_dpp v67, v67, v67 quad_perm:[2,3,0,1] row_mask:0xf bank_mask:0xf bound_ctrl:1
	v_add_u32_dpp v64, v64, v64 row_half_mirror row_mask:0xf bank_mask:0xf bound_ctrl:1
	v_add_u32_dpp v65, v65, v65 row_half_mirror row_mask:0xf bank_mask:0xf bound_ctrl:1
	v_add_u32_dpp v66, v66, v66 row_half_mirror row_mask:0xf bank_mask:0xf bound_ctrl:1
	v_add_u32_dpp v67, v67, v67 row_half_mirror row_mask:0xf bank_mask:0xf bound_ctrl:1
	v_cvt_f32_i32_e32 v72, v64
	v_cvt_f32_i32_e32 v73, v65
	v_cvt_f32_i32_e32 v74, v66
	v_cvt_f32_i32_e32 v75, v67
	v_pk_mul_f32 v[72:73], v[52:53], v[72:73] op_sel_hi:[0,1]
	v_pk_mul_f32 v[74:75], v[52:53], v[74:75] op_sel_hi:[0,1]
	v_and_b32_e32 v56, s21, v208
	v_and_b32_e32 v57, s23, v208
	v_and_b32_e32 v58, s21, v212
	v_and_b32_e32 v59, s23, v212
	v_and_b32_e32 v60, s21, v216
	v_and_b32_e32 v61, s23, v216
	v_and_b32_e32 v62, s21, v220
	v_and_b32_e32 v63, s23, v220
	v_dot4_i32_i8 v64, v56, v32, v85
	v_dot4_i32_i8 v86, v57, v33, 0
	v_dot4_i32_i8 v65, v58, v32, v85
	v_dot4_i32_i8 v87, v59, v33, 0
	v_dot4_i32_i8 v66, v60, v32, v85
	v_dot4_i32_i8 v88, v61, v33, 0
	v_dot4_i32_i8 v67, v62, v32, v85
	v_dot4_i32_i8 v89, v63, v33, 0
	v_and_b32_e32 v56, s21, v209
	v_and_b32_e32 v57, s23, v209
	v_and_b32_e32 v58, s21, v213
	v_and_b32_e32 v59, s23, v213
	v_and_b32_e32 v60, s21, v217
	v_and_b32_e32 v61, s23, v217
	v_and_b32_e32 v62, s21, v221
	v_and_b32_e32 v63, s23, v221
	v_dot4c_i32_i8_e32 v64, v56, v34
	v_dot4c_i32_i8_e32 v86, v57, v35
	v_dot4c_i32_i8_e32 v65, v58, v34
	v_dot4c_i32_i8_e32 v87, v59, v35
	v_dot4c_i32_i8_e32 v66, v60, v34
	v_dot4c_i32_i8_e32 v88, v61, v35
	v_dot4c_i32_i8_e32 v67, v62, v34
	v_dot4c_i32_i8_e32 v89, v63, v35
	v_and_b32_e32 v56, s21, v210
	v_and_b32_e32 v57, s23, v210
	v_and_b32_e32 v58, s21, v214
	v_and_b32_e32 v59, s23, v214
	v_and_b32_e32 v60, s21, v218
	v_and_b32_e32 v61, s23, v218
	v_and_b32_e32 v62, s21, v222
	v_and_b32_e32 v63, s23, v222
	v_dot4c_i32_i8_e32 v64, v56, v36
	v_dot4c_i32_i8_e32 v86, v57, v37
	v_dot4c_i32_i8_e32 v65, v58, v36
	v_dot4c_i32_i8_e32 v87, v59, v37
	v_dot4c_i32_i8_e32 v66, v60, v36
	v_dot4c_i32_i8_e32 v88, v61, v37
	v_dot4c_i32_i8_e32 v67, v62, v36
	v_dot4c_i32_i8_e32 v89, v63, v37
	v_and_b32_e32 v56, s21, v211
	v_and_b32_e32 v57, s23, v211
	v_and_b32_e32 v58, s21, v215
	v_and_b32_e32 v59, s23, v215
	v_and_b32_e32 v60, s21, v219
	v_and_b32_e32 v61, s23, v219
	v_and_b32_e32 v62, s21, v223
	v_and_b32_e32 v63, s23, v223
	v_dot4c_i32_i8_e32 v64, v56, v38
	v_dot4c_i32_i8_e32 v86, v57, v39
	v_dot4c_i32_i8_e32 v65, v58, v38
	v_dot4c_i32_i8_e32 v87, v59, v39
	v_dot4c_i32_i8_e32 v66, v60, v38
	v_dot4c_i32_i8_e32 v88, v61, v39
	v_dot4c_i32_i8_e32 v67, v62, v38
; __device__ __forceinline__ void phase_peer_u(const Params& p, int layer, int xs, int wid0, int wstride, char* smraw) {
;     ...
;     float pr[16];
; #pragma unroll
;     for (int i = 0; i < 16; ++i) {
;       int a = 0;
; #pragma unroll
;       for (int m = 0; m < 4; ++m) {
;         const unsigned dw = q[i][m];
;         a = __builtin_amdgcn_sdot4((int)(dw & 0x0f0f0f0fu), xq[2 * m], a, false);
;         a = __builtin_amdgcn_sdot4((int)((dw >> 4) & 0x0f0f0f0fu), xq[2 * m + 1], a, false);
;       }
;       a -= corr;
;       a += __builtin_amdgcn_update_dpp(0, a, 0xB1, 0xF, 0xF, true);
;       a += __builtin_amdgcn_update_dpp(0, a, 0x4E, 0xF, 0xF, true);
;       a += __builtin_amdgcn_update_dpp(0, a, 0x141, 0xF, 0xF, true);
;       pr[i] = (float)a * sx;
;     }
;     if (j == 0) {
;       f32x4* dst = (f32x4*)((char*)p.actp + ((unsigned)t * 4096u + (unsigned)(sl * 512 + g * 64)));
; #pragma unroll
;       for (int q4 = 0; q4 < 4; ++q4) dst[q4] = f32x4{pr[q4 * 4], pr[q4 * 4 + 1], pr[q4 * 4 + 2], pr[q4 * 4 + 3]};
;     }
;     ...
;     compute(tt, qB, xB);
;     tt += wstride;
;   }
	v_dot4c_i32_i8_e32 v89, v63, v39
	v_ashrrev_i32_e32 v86, 4, v86
	v_ashrrev_i32_e32 v87, 4, v87
	v_ashrrev_i32_e32 v88, 4, v88
	v_ashrrev_i32_e32 v89, 4, v89
	v_add_u32_e32 v64, v64, v86
	v_add_u32_e32 v65, v65, v87
	v_add_u32_e32 v66, v66, v88
	v_add_u32_e32 v67, v67, v89
	v_add_u32_dpp v64, v64, v64 quad_perm:[1,0,3,2] row_mask:0xf bank_mask:0xf bound_ctrl:1
	v_add_u32_dpp v65, v65, v65 quad_perm:[1,0,3,2] row_mask:0xf bank_mask:0xf bound_ctrl:1
	v_add_u32_dpp v66, v66, v66 quad_perm:[1,0,3,2] row_mask:0xf bank_mask:0xf bound_ctrl:1
	v_add_u32_dpp v67, v67, v67 quad_perm:[1,0,3,2] row_mask:0xf bank_mask:0xf bound_ctrl:1
	v_add_u32_dpp v64, v64, v64 quad_perm:[2,3,0,1] row_mask:0xf bank_mask:0xf bound_ctrl:1
	v_add_u32_dpp v65, v65, v65 quad_perm:[2,3,0,1] row_mask:0xf bank_mask:0xf bound_ctrl:1
	v_add_u32_dpp v66, v66, v66 quad_perm:[2,3,0,1] row_mask:0xf bank_mask:0xf bound_ctrl:1
	v_add_u32_dpp v67, v67, v67 quad_perm:[2,3,0,1] row_mask:0xf bank_mask:0xf bound_ctrl:1
	v_add_u32_dpp v64, v64, v64 row_half_mirror row_mask:0xf bank_mask:0xf bound_ctrl:1
	v_add_u32_dpp v65, v65, v65 row_half_mirror row_mask:0xf bank_mask:0xf bound_ctrl:1
	v_add_u32_dpp v66, v66, v66 row_half_mirror row_mask:0xf bank_mask:0xf bound_ctrl:1
	v_add_u32_dpp v67, v67, v67 row_half_mirror row_mask:0xf bank_mask:0xf bound_ctrl:1
	v_cvt_f32_i32_e32 v76, v64
	v_cvt_f32_i32_e32 v77, v65
	v_cvt_f32_i32_e32 v78, v66
	v_cvt_f32_i32_e32 v79, v67
	v_pk_mul_f32 v[76:77], v[52:53], v[76:77] op_sel_hi:[0,1]
	v_pk_mul_f32 v[78:79], v[52:53], v[78:79] op_sel_hi:[0,1]
	v_and_b32_e32 v56, s21, v224
	v_and_b32_e32 v57, s23, v224
	v_and_b32_e32 v58, s21, v228
	v_and_b32_e32 v59, s23, v228
	v_and_b32_e32 v60, s21, v232
	v_and_b32_e32 v61, s23, v232
	v_and_b32_e32 v62, s21, v236
	v_and_b32_e32 v63, s23, v236
	v_dot4_i32_i8 v64, v56, v32, v85
	v_dot4_i32_i8 v86, v57, v33, 0
	v_dot4_i32_i8 v65, v58, v32, v85
	v_dot4_i32_i8 v87, v59, v33, 0
	v_dot4_i32_i8 v66, v60, v32, v85
	v_dot4_i32_i8 v88, v61, v33, 0
	v_dot4_i32_i8 v67, v62, v32, v85
	v_dot4_i32_i8 v89, v63, v33, 0
	v_and_b32_e32 v56, s21, v225
	v_and_b32_e32 v57, s23, v225
	v_and_b32_e32 v58, s21, v229
	v_and_b32_e32 v59, s23, v229
	v_and_b32_e32 v60, s21, v233
	v_and_b32_e32 v61, s23, v233
	v_and_b32_e32 v62, s21, v237
	v_and_b32_e32 v63, s23, v237
	v_dot4c_i32_i8_e32 v64, v56, v34
	v_dot4c_i32_i8_e32 v86, v57, v35
	v_dot4c_i32_i8_e32 v65, v58, v34
	v_dot4c_i32_i8_e32 v87, v59, v35
	v_dot4c_i32_i8_e32 v66, v60, v34
	v_dot4c_i32_i8_e32 v88, v61, v35
	v_dot4c_i32_i8_e32 v67, v62, v34
	v_dot4c_i32_i8_e32 v89, v63, v35
	v_and_b32_e32 v56, s21, v226
	v_and_b32_e32 v57, s23, v226
	v_and_b32_e32 v58, s21, v230
	v_and_b32_e32 v59, s23, v230
	v_and_b32_e32 v60, s21, v234
	v_and_b32_e32 v61, s23, v234
	v_and_b32_e32 v62, s21, v238
	v_and_b32_e32 v63, s23, v238
	v_dot4c_i32_i8_e32 v64, v56, v36
	v_dot4c_i32_i8_e32 v86, v57, v37
	v_dot4c_i32_i8_e32 v65, v58, v36
	v_dot4c_i32_i8_e32 v87, v59, v37
	v_dot4c_i32_i8_e32 v66, v60, v36
	v_dot4c_i32_i8_e32 v88, v61, v37
	v_dot4c_i32_i8_e32 v67, v62, v36
	v_dot4c_i32_i8_e32 v89, v63, v37
	v_and_b32_e32 v56, s21, v227
	v_and_b32_e32 v57, s23, v227
	v_and_b32_e32 v58, s21, v231
	v_and_b32_e32 v59, s23, v231
	v_and_b32_e32 v60, s21, v235
	v_and_b32_e32 v61, s23, v235
	v_and_b32_e32 v62, s21, v239
	v_and_b32_e32 v63, s23, v239
	v_dot4c_i32_i8_e32 v64, v56, v38
	v_dot4c_i32_i8_e32 v86, v57, v39
	v_dot4c_i32_i8_e32 v65, v58, v38
	v_dot4c_i32_i8_e32 v87, v59, v39
	v_dot4c_i32_i8_e32 v66, v60, v38
	v_dot4c_i32_i8_e32 v88, v61, v39
	v_dot4c_i32_i8_e32 v67, v62, v38
	v_dot4c_i32_i8_e32 v89, v63, v39
	v_ashrrev_i32_e32 v86, 4, v86
	v_ashrrev_i32_e32 v87, 4, v87
	v_ashrrev_i32_e32 v88, 4, v88
	v_ashrrev_i32_e32 v89, 4, v89
	v_add_u32_e32 v64, v64, v86
	v_add_u32_e32 v65, v65, v87
	v_add_u32_e32 v66, v66, v88
	v_add_u32_e32 v67, v67, v89
	v_add_u32_dpp v64, v64, v64 quad_perm:[1,0,3,2] row_mask:0xf bank_mask:0xf bound_ctrl:1
	v_add_u32_dpp v65, v65, v65 quad_perm:[1,0,3,2] row_mask:0xf bank_mask:0xf bound_ctrl:1
	v_add_u32_dpp v66, v66, v66 quad_perm:[1,0,3,2] row_mask:0xf bank_mask:0xf bound_ctrl:1
	v_add_u32_dpp v67, v67, v67 quad_perm:[1,0,3,2] row_mask:0xf bank_mask:0xf bound_ctrl:1
	v_add_u32_dpp v64, v64, v64 quad_perm:[2,3,0,1] row_mask:0xf bank_mask:0xf bound_ctrl:1
	v_add_u32_dpp v65, v65, v65 quad_perm:[2,3,0,1] row_mask:0xf bank_mask:0xf bound_ctrl:1
	v_add_u32_dpp v66, v66, v66 quad_perm:[2,3,0,1] row_mask:0xf bank_mask:0xf bound_ctrl:1
	v_add_u32_dpp v67, v67, v67 quad_perm:[2,3,0,1] row_mask:0xf bank_mask:0xf bound_ctrl:1
	v_add_u32_dpp v64, v64, v64 row_half_mirror row_mask:0xf bank_mask:0xf bound_ctrl:1
	v_add_u32_dpp v65, v65, v65 row_half_mirror row_mask:0xf bank_mask:0xf bound_ctrl:1
	v_add_u32_dpp v66, v66, v66 row_half_mirror row_mask:0xf bank_mask:0xf bound_ctrl:1
	v_add_u32_dpp v67, v67, v67 row_half_mirror row_mask:0xf bank_mask:0xf bound_ctrl:1
	v_cvt_f32_i32_e32 v80, v64
	v_cvt_f32_i32_e32 v81, v65
	v_cvt_f32_i32_e32 v82, v66
	v_cvt_f32_i32_e32 v83, v67
	v_pk_mul_f32 v[80:81], v[52:53], v[80:81] op_sel_hi:[0,1]
	v_pk_mul_f32 v[82:83], v[52:53], v[82:83] op_sel_hi:[0,1]
	s_lshl_b32 s70, s60, 1
	s_add_u32 s70, s70, s28
	s_lshl_b32 s70, s70, 12
	s_add_u32 s70, s70, s68
	s_mov_b64 s[74:75], exec
	s_and_b64 exec, exec, s[72:73]
	v_add_u32_e32 v9, s70, v5
	global_store_dwordx4 v9, v[68:71], s[64:65]
	global_store_dwordx4 v9, v[72:75], s[64:65] offset:16
	global_store_dwordx4 v9, v[76:79], s[64:65] offset:32
	global_store_dwordx4 v9, v[80:83], s[64:65] offset:48
	s_mov_b64 exec, s[74:75]
	s_mov_b32 s60, s62
	s_cmp_lt_u32 s60, s61
	s_cbranch_scc1 .Lmy_pu0_bodyA
